# S5 pass-B chunk order mirrored on alternate rounds (load balance) + NSA compressed-branch pass 2 V loads hoisted next to K loads
# speedup vs baseline: 1.0095x; 1.0095x over previous
; template <bool PASSB>
; DI void s5_item(const Params& p, int oi, int witem, float* wl  ) {
;     ...
;   const int bgi = witem >> 8, c = witem & 255, b = bgi >> 5, g = bgi & 31;
;   const int gp = g * 64 + lane;
;   const float lre = pre[gp * 2], lim = pre[gp * 2 + 1];
;   float bre[16], bim[16];
; #pragma unroll
;   for (int h = 0; h < 16; ++h) { bre[h] = pre[8192 + (g * 32 + h) * 64 + lane]; bim[h] = pre[8192 + (g * 32 + 16 + h) * 64 + lane]; }
;   const size_t tg0 = (size_t)b * L + c * 64;
;   __builtin_amdgcn_wave_barrier();
; #pragma unroll
;   for (int i = 0; i < 4; ++i) {
;     const int idx = i * 64 + lane, tt = idx >> 2, q = idx & 3;
;     *(f32x4*)(wl + tt * 16 + q * 4) = *(const f32x4*)(us5 + (tg0 + tt) * 512 + g * 16 + q * 4);
;   }
;   __builtin_amdgcn_wave_barrier();
;   __builtin_amdgcn_s_waitcnt(0xc07f);
;   float xre = 0.f, xim = 0.f;
;   if (PASSB) {
;     const float Lre = pre[4096 + gp * 2], Lim = pre[4096 + gp * 2 + 1];
;     const float* Sp = S + (size_t)bgi * 256 * 128;
;     int cc = 0;
;     for (; cc + 8 <= c; cc += 8) {
.LBB0_152:
	s_lshl_b32 s3, s2, 2
	s_add_i32 s4, s3, s49
	v_mov_b32_e32 v7, v183
	s_ashr_i32 s24, s4, 8
	s_and_b32 s3, s24, 31
	s_waitcnt vmcnt(8)
	v_and_b32_e32 v16, 63, v7
	v_lshlrev_b32_e32 v0, 3, v16
	s_lshl_b32 s5, s3, 11
	v_lshl_or_b32 v176, s3, 9, v0
	v_or_b32_e32 v0, 0x2000, v16
	v_or_b32_e32 v1, 0x2400, v16
	s_or_b32 s25, s5, 64
	v_add_lshl_u32 v4, v0, s25, 2
	v_add_lshl_u32 v5, v1, s25, 2
	s_or_b32 s25, s5, 0x80
	v_add_lshl_u32 v6, v0, s25, 2
	s_waitcnt vmcnt(4)
	v_add_lshl_u32 v8, v1, s25, 2
	s_or_b32 s25, s5, 0xc0
	v_add_lshl_u32 v2, v0, s5, 2
	v_add_lshl_u32 v3, v1, s5, 2
	v_add_lshl_u32 v9, v0, s25, 2
	v_add_lshl_u32 v10, v1, s25, 2
	s_or_b32 s25, s5, 0x100
	global_load_dword v20, v2, s[40:41]
	global_load_dword v21, v3, s[40:41]
	global_load_dword v22, v4, s[40:41]
	global_load_dword v23, v5, s[40:41]
	global_load_dword v24, v6, s[40:41]
	global_load_dword v25, v8, s[40:41]
	global_load_dword v26, v9, s[40:41]
	global_load_dword v27, v10, s[40:41]
	v_add_lshl_u32 v2, v0, s25, 2
	v_add_lshl_u32 v3, v1, s25, 2
	s_or_b32 s25, s5, 0x140
	v_add_lshl_u32 v4, v0, s25, 2
	v_add_lshl_u32 v5, v1, s25, 2
	s_or_b32 s25, s5, 0x180
	v_add_lshl_u32 v6, v0, s25, 2
	v_add_lshl_u32 v8, v1, s25, 2
	s_or_b32 s25, s5, 0x1c0
	v_add_lshl_u32 v9, v0, s25, 2
	v_add_lshl_u32 v10, v1, s25, 2
	s_or_b32 s25, s5, 0x200
	global_load_dword v28, v2, s[40:41]
	global_load_dword v29, v3, s[40:41]
	global_load_dword v30, v4, s[40:41]
	global_load_dword v31, v5, s[40:41]
	global_load_dword v32, v6, s[40:41]
	global_load_dword v33, v8, s[40:41]
	global_load_dword v34, v9, s[40:41]
	global_load_dword v35, v10, s[40:41]
	v_add_lshl_u32 v2, v0, s25, 2
	v_add_lshl_u32 v3, v1, s25, 2
	s_or_b32 s25, s5, 0x240
	v_add_lshl_u32 v4, v0, s25, 2
	v_add_lshl_u32 v5, v1, s25, 2
	s_or_b32 s25, s5, 0x280
	v_add_lshl_u32 v6, v0, s25, 2
	v_add_lshl_u32 v8, v1, s25, 2
	s_or_b32 s25, s5, 0x2c0
	v_add_lshl_u32 v9, v0, s25, 2
	v_add_lshl_u32 v10, v1, s25, 2
	s_or_b32 s25, s5, 0x300
	global_load_dword v36, v2, s[40:41]
	global_load_dword v37, v3, s[40:41]
	global_load_dword v38, v4, s[40:41]
	global_load_dword v39, v5, s[40:41]
	global_load_dword v40, v6, s[40:41]
	global_load_dword v41, v8, s[40:41]
	global_load_dword v42, v9, s[40:41]
	global_load_dword v43, v10, s[40:41]
	v_add_lshl_u32 v2, v0, s25, 2
	v_add_lshl_u32 v3, v1, s25, 2
	s_or_b32 s25, s5, 0x340
	s_and_b32 s27, s4, 0xff
	s_bfe_u32 s30, s4, 0x1000b
	s_mul_i32 s30, s30, 0xff
	s_xor_b32 s27, s27, s30
	v_add_lshl_u32 v4, v0, s25, 2
	v_add_lshl_u32 v5, v1, s25, 2
	s_or_b32 s25, s5, 0x380
	s_or_b32 s5, s5, 0x3c0
	s_ashr_i32 s4, s4, 13
	v_add_lshl_u32 v6, v0, s25, 2
	v_add_lshl_u32 v8, v1, s25, 2
	v_add_lshl_u32 v0, v0, s5, 2
	v_add_lshl_u32 v1, v1, s5, 2
	s_ashr_i32 s5, s4, 31
	s_lshl_b64 s[4:5], s[4:5], 14
	s_lshl_b32 s25, s27, 6
	s_or_b32 s4, s4, s25
	s_lshl_b32 s25, s3, 6
	global_load_dword v44, v2, s[40:41]
	global_load_dword v45, v3, s[40:41]
	global_load_dword v46, v4, s[40:41]
	global_load_dword v47, v5, s[40:41]
	global_load_dword v48, v6, s[40:41]
	global_load_dword v49, v8, s[40:41]
	global_load_dword v50, v0, s[40:41]
	global_load_dword v51, v1, s[40:41]
	s_add_u32 s30, s44, s25
	v_lshlrev_b32_e32 v0, 4, v7
	s_addc_u32 s31, s45, 0
	v_and_b32_e32 v4, 48, v0
	v_mov_b32_e32 v5, v177
	v_lshl_add_u64 v[0:1], s[30:31], 0, v[4:5]
	v_bfe_u32 v5, v7, 2, 4
	v_or_b32_e32 v2, s4, v5
	v_mov_b32_e32 v3, s5
	v_lshlrev_b64 v[8:9], 11, v[2:3]
	v_or_b32_e32 v2, 64, v16
	v_lshrrev_b32_e32 v6, 2, v2
	v_or_b32_e32 v2, s4, v6
	v_or_b32_e32 v17, 32, v5
	v_lshlrev_b64 v[10:11], 11, v[2:3]
	v_or_b32_e32 v2, s4, v17
	v_or_b32_e32 v58, 48, v5
	v_lshlrev_b64 v[12:13], 11, v[2:3]
	v_or_b32_e32 v2, s4, v58
	v_lshl_add_u64 v[8:9], v[0:1], 0, v[8:9]
	v_lshl_add_u64 v[10:11], v[0:1], 0, v[10:11]
	v_lshl_add_u64 v[12:13], v[0:1], 0, v[12:13]
	v_lshlrev_b64 v[2:3], 11, v[2:3]
	v_lshl_add_u64 v[18:19], v[0:1], 0, v[2:3]
	global_load_dwordx2 v[52:53], v176, s[40:41]
	global_load_dwordx4 v[0:3], v[8:9], off
	s_nop 0
	global_load_dwordx4 v[8:11], v[10:11], off
	s_nop 0
	global_load_dwordx4 v[12:15], v[12:13], off
	s_nop 0
	global_load_dwordx4 v[54:57], v[18:19], off
	v_add_u32_e32 v4, s42, v4
	v_lshl_add_u64 v[18:19], s[40:41], 0, v[176:177]
	v_lshl_add_u32 v5, v5, 6, v4
	v_lshl_add_u32 v6, v6, 6, v4
	v_lshl_add_u32 v17, v17, 6, v4
	v_lshl_add_u32 v4, v58, 6, v4
	s_ashr_i32 s25, s24, 31
	s_lshl_b64 s[24:25], s[24:25], 17
	s_cmp_lt_u32 s27, 8
	s_mov_b32 s30, 0
	s_waitcnt vmcnt(3)
	ds_write_b128 v5, v[0:3]
	s_waitcnt vmcnt(2)
	ds_write_b128 v6, v[8:11]
	s_waitcnt vmcnt(1)
	ds_write_b128 v17, v[12:15]
	s_waitcnt vmcnt(0)
	ds_write_b128 v4, v[54:57]
	v_add_co_u32_e32 v0, vcc, 0x4000, v18
	s_waitcnt lgkmcnt(0)
	s_nop 0
	v_addc_co_u32_e32 v1, vcc, 0, v19, vcc
	global_load_dwordx2 v[0:1], v[0:1], off
	s_cbranch_scc1 .LBB0_156
	s_add_u32 s30, s43, s24
	v_lshlrev_b32_e32 v176, 2, v16
	s_addc_u32 s31, s46, s25
	v_mov_b32_e32 v54, 0
	s_waitcnt vmcnt(0)
	v_pk_mov_b32 v[2:3], v[0:1], v[0:1] op_sel:[1,0]
	v_lshl_add_u64 v[4:5], s[30:31], 0, v[176:177]
	s_mov_b32 s30, 0
	v_mov_b32_e32 v55, v54

; #define MFMA16(a, b, c) __builtin_amdgcn_mfma_f32_16x16x32_bf16((a), (b), (c), 0, 0, 0)
; DI float ex2(float x) { return __builtin_amdgcn_exp2f(x); }
; DI float xor1(float v) { return dppf<0xB1>(v); }
; DI float xor2(float v) { return dppf<0x4E>(v); }
; DI void attn_scores(const bfr* Kp, int key0, const bf16x8& q0, const bf16x8& q1, int r, int quad, float* sc) {
;   const bfr* kr = Kp + (size_t)key0 * 64 + (quad * 16 + r) * 8;
;   const bf16x8 a00 = ld8(kr), a01 = ld8(kr + 512), a10 = ld8(kr + 1024), a11 = ld8(kr + 1536);
;   f32x4 s0 = {0.f, 0.f, 0.f, 0.f}, s1 = {0.f, 0.f, 0.f, 0.f};
;   s0 = MFMA16(a00, q0, s0); s0 = MFMA16(a01, q1, s0);
;   s1 = MFMA16(a10, q0, s1); s1 = MFMA16(a11, q1, s1);
; #pragma unroll
;   for (int i = 0; i < 4; ++i) { sc[i] = s0[i]; sc[4 + i] = s1[i]; }
; }
; DI void attn_pv(AttnSt& s, const bfr* VTp, int key0, const bf16x8& pb, int r, int quad) {
;   const bfr* vb = VTp + (size_t)key0 * 64 + (quad * 16 + r) * 8;
; #pragma unroll
;   for (int dt = 0; dt < 4; ++dt) s.o[dt] = MFMA16(ld8(vb + dt * 512), pb, s.o[dt]);
; }
; DI void nsa_item(const Params& p, int witem, float* wl) {
;     ...
;     for (int k0 = 0; k0 <= nmax; k0 += 32) {
;       float sc[8];
;       attn_scores(Kp, k0, q0, q1, r, quad, sc);
; #pragma unroll
;       for (int i = 0; i < 8; ++i) { const int key = k0 + (i >> 2) * 16 + quad * 4 + (i & 3); sc[i] = key <= hi ? ex2(sc[i] - m) * inv : 0.f; }
;       const bf16x8 pb = pack8(sc[0], sc[1], sc[2], sc[3], sc[4], sc[5], sc[6], sc[7]);
;       attn_pv(s, VTp, k0, pb, r, quad);
; #pragma unroll
;       for (int i = 0; i < 8; ++i) { sc[i] += xor1(sc[i]); sc[i] += xor2(sc[i]); }
;       if ((r & 3) == 0) {
;         const int j0 = (k0 >> 2) + quad;
;         own4[tok * 256 + j0] = sc[0] + sc[1] + sc[2] + sc[3]; lastp[tok * 256 + j0] = sc[3];
;         own4[tok * 256 + j0 + 4] = sc[4] + sc[5] + sc[6] + sc[7]; lastp[tok * 256 + j0 + 4] = sc[7];
;       }
;     }
.LBB0_338:
	global_load_dwordx4 v[24:27], v[36:37], off
	global_load_dwordx4 v[44:47], v[36:37], off offset:1024
	global_load_dwordx4 v[48:51], v[36:37], off offset:2048
	global_load_dwordx4 v[52:55], v[36:37], off offset:3072
	s_mov_b64 s[24:25], 0x80000
	v_lshl_add_u64 v[72:73], v[36:37], 0, s[24:25]
	global_load_dwordx4 v[60:63], v[72:73], off
	global_load_dwordx4 v[64:67], v[72:73], off offset:1024
	global_load_dwordx4 v[68:71], v[72:73], off offset:2048
	global_load_dwordx4 v[72:75], v[72:73], off offset:3072
	v_cmp_le_i32_e64 s[40:41], v113, v41
	s_waitcnt vmcnt(7)
	v_mfma_f32_16x16x32_bf16 v[24:27], v[24:27], v[0:3], 0
	s_waitcnt vmcnt(6)
	v_mfma_f32_16x16x32_bf16 v[24:27], v[44:47], v[4:7], v[24:27]
	s_waitcnt vmcnt(5)
	v_mfma_f32_16x16x32_bf16 v[44:47], v[48:51], v[0:3], 0
	s_waitcnt vmcnt(4)
	v_mfma_f32_16x16x32_bf16 v[44:47], v[52:55], v[4:7], v[44:47]
	s_nop 3
	v_sub_f32_e32 v24, v24, v42
	v_exp_f32_e32 v24, v24
	s_nop 0
	v_mul_f32_e32 v24, v34, v24
	v_cndmask_b32_e64 v48, 0, v24, s[40:41]
	v_sub_f32_e32 v24, v25, v42
	v_exp_f32_e32 v24, v24
	v_cmp_lt_i32_e64 s[40:41], v113, v41
	v_sub_f32_e32 v25, v27, v42
	v_exp_f32_e32 v25, v25
	v_mul_f32_e32 v24, v34, v24
	v_cndmask_b32_e64 v49, 0, v24, s[40:41]
	v_sub_f32_e32 v24, v26, v42
	v_exp_f32_e32 v24, v24
	v_cmp_le_i32_e64 s[40:41], v29, v41
	v_pk_mul_f32 v[24:25], v[34:35], v[24:25]
	s_nop 0
	v_cndmask_b32_e64 v50, 0, v25, s[40:41]
	v_cmp_le_i32_e64 s[40:41], v28, v41
	v_sub_f32_e32 v25, v45, v42
	v_exp_f32_e32 v25, v25
	v_cndmask_b32_e64 v51, 0, v24, s[40:41]
	v_sub_f32_e32 v24, v44, v42
	v_exp_f32_e32 v24, v24
	v_cmp_le_i32_e64 s[40:41], v31, v41
	v_pk_mul_f32 v[24:25], v[34:35], v[24:25]
	s_nop 0
	v_cndmask_b32_e64 v54, 0, v25, s[40:41]
	v_cmp_le_i32_e64 s[40:41], v30, v41
	v_sub_f32_e32 v25, v47, v42
	v_exp_f32_e32 v25, v25
	v_cndmask_b32_e64 v52, 0, v24, s[40:41]
	v_sub_f32_e32 v24, v46, v42
	v_exp_f32_e32 v24, v24
	v_cmp_le_i32_e64 s[40:41], v33, v41
	v_cvt_pk_bf16_f32 v26, v52, v54
	v_add_f32_dpp v46, v49, v49 quad_perm:[1,0,3,2] row_mask:0xf bank_mask:0xf bound_ctrl:1
	v_pk_mul_f32 v[24:25], v[34:35], v[24:25]
	v_add_f32_dpp v52, v52, v52 quad_perm:[1,0,3,2] row_mask:0xf bank_mask:0xf bound_ctrl:1
	v_cndmask_b32_e64 v58, 0, v25, s[40:41]
	v_cmp_le_i32_e64 s[40:41], v32, v41
	v_cvt_pk_bf16_f32 v25, v51, v50
	v_add_f32_dpp v50, v50, v50 quad_perm:[1,0,3,2] row_mask:0xf bank_mask:0xf bound_ctrl:1
	v_cndmask_b32_e64 v56, 0, v24, s[40:41]
	v_cvt_pk_bf16_f32 v24, v48, v49
	v_cvt_pk_bf16_f32 v27, v56, v58
	v_add_f32_dpp v44, v48, v48 quad_perm:[1,0,3,2] row_mask:0xf bank_mask:0xf bound_ctrl:1
	v_add_f32_dpp v48, v51, v51 quad_perm:[1,0,3,2] row_mask:0xf bank_mask:0xf bound_ctrl:1
	v_add_f32_dpp v54, v54, v54 quad_perm:[1,0,3,2] row_mask:0xf bank_mask:0xf bound_ctrl:1
	v_add_f32_dpp v56, v56, v56 quad_perm:[1,0,3,2] row_mask:0xf bank_mask:0xf bound_ctrl:1
	v_add_f32_dpp v58, v58, v58 quad_perm:[1,0,3,2] row_mask:0xf bank_mask:0xf bound_ctrl:1
	v_mov_b32_dpp v45, v44 quad_perm:[2,3,0,1] row_mask:0xf bank_mask:0xf bound_ctrl:1
	v_mov_b32_dpp v47, v46 quad_perm:[2,3,0,1] row_mask:0xf bank_mask:0xf bound_ctrl:1
	v_mov_b32_dpp v49, v48 quad_perm:[2,3,0,1] row_mask:0xf bank_mask:0xf bound_ctrl:1
	v_mov_b32_dpp v51, v50 quad_perm:[2,3,0,1] row_mask:0xf bank_mask:0xf bound_ctrl:1
	v_mov_b32_dpp v53, v52 quad_perm:[2,3,0,1] row_mask:0xf bank_mask:0xf bound_ctrl:1
	v_mov_b32_dpp v55, v54 quad_perm:[2,3,0,1] row_mask:0xf bank_mask:0xf bound_ctrl:1
	v_mov_b32_dpp v57, v56 quad_perm:[2,3,0,1] row_mask:0xf bank_mask:0xf bound_ctrl:1
	v_mov_b32_dpp v59, v58 quad_perm:[2,3,0,1] row_mask:0xf bank_mask:0xf bound_ctrl:1
	s_waitcnt vmcnt(3)
	v_mfma_f32_16x16x32_bf16 v[8:11], v[60:63], v[24:27], v[8:11]
	s_waitcnt vmcnt(2)
	v_mfma_f32_16x16x32_bf16 v[12:15], v[64:67], v[24:27], v[12:15]
	s_waitcnt vmcnt(1)
	v_mfma_f32_16x16x32_bf16 v[16:19], v[68:71], v[24:27], v[16:19]
	s_waitcnt vmcnt(0)
	v_mfma_f32_16x16x32_bf16 v[20:23], v[72:75], v[24:27], v[20:23]
	s_and_saveexec_b64 s[24:25], vcc
	s_cbranch_execz .LBB0_337
	v_add_f32_e32 v26, v54, v55
	v_add_f32_e32 v27, v52, v53
	v_add_f32_e32 v46, v46, v47
	v_add_f32_e32 v44, v44, v45
	v_add_f32_e32 v25, v56, v57
	v_add_f32_e32 v48, v48, v49
	v_add_f32_e32 v44, v44, v46
	v_add_f32_e32 v26, v27, v26
	v_add_f32_e32 v24, v58, v59
	v_add_f32_e32 v50, v50, v51
	v_add_f32_e32 v44, v44, v48
	v_add_f32_e32 v25, v26, v25
	v_add_f32_e32 v44, v44, v50
	v_add_u32_e32 v45, s34, v43
	v_add_f32_e32 v25, v25, v24
	ds_write2_b32 v45, v44, v25 offset1:4
	v_add_u32_e32 v25, 0x1000, v45
	ds_write2_b32 v25, v50, v24 offset1:4
	s_branch .LBB0_337
